# speedup vs baseline: 1.0083x; 1.0083x over previous
; #define PG8_STAGE(bufoff, gbase, voff) do { _Pragma("unroll") for (int _i = 0; _i < 2; ++_i) \
;         __builtin_amdgcn_global_load_lds((const unsigned*)((const char*)(gbase) + (voff)[_i]), (PG8_LAS unsigned*)(lds + (bufoff) + ldsw + _i * 8192), 16, 0, 0); } while (0)
; #define PG8_LDA(dst, b, h) do { _Pragma("unroll") for (int m = 0; m < 4; ++m) _Pragma("unroll") for (int k = 0; k < 2; ++k) dst[m][k] = *(const PG8_LAS bf16x8*)(lds + PG8_SA(b, h) + aoff + m * 2048 + k * 1024); } while (0)
; #define PG8_LDB(dst, b, h) do { _Pragma("unroll") for (int n = 0; n < 2; ++n) _Pragma("unroll") for (int k = 0; k < 2; ++k) dst[n][k] = *(const PG8_LAS bf16x8*)(lds + PG8_SB(b, h) + boff + n * 2048 + k * 1024); } while (0)
; #define PG8_MMA(ai, bj, At, Bt) do { __builtin_amdgcn_s_setprio(1); _Pragma("unroll") for (int m = 0; m < 4; ++m) _Pragma("unroll") for (int n = 0; n < 2; ++n) _Pragma("unroll") for (int k = 0; k < 2; ++k) \
;         acc[ai][bj][m][n] = __builtin_amdgcn_mfma_f32_16x16x32_bf16(Bt[n][k], At[m][k], acc[ai][bj][m][n], 0, 0, 0); __builtin_amdgcn_s_setprio(0); } while (0)
; #define PG8_WAIT_V(n) asm volatile("s_waitcnt vmcnt(" #n ")" ::: "memory")
; #define PG8_WAIT_L(n) asm volatile("s_waitcnt lgkmcnt(" #n ")" ::: "memory")
; #define PG8_BAR __builtin_amdgcn_s_barrier()
; #define PG8_SCHED __builtin_amdgcn_sched_barrier(0)
; template <class Epi, class Sched, bool ALIGN_EPI = false, bool SP2 = false>
; __device__ __forceinline__ void gemm_phase(PG8_LAS unsigned char* lds, const Gemm g, const Sched& S, const Epi& E) {
;     ...
;             PG8_LDB(B0, 0, 0); PG8_LDB(B1, 0, 1); PG8_SCHED; PG8_LDA(At, 0, 0); PG8_STAGE(PG8_SA(1, 1), a1 + hstep, voffA);
;             PG8_WAIT_V(8); PG8_WAIT_L(0); PG8_BAR; PG8_MMA(0, 0, At, B0); PG8_MMA(0, 1, At, B1); PG8_BAR; PG8_SCHED;
;             PG8_LDA(At, 0, 1); PG8_STAGE(PG8_SB(0, 0), b2, voffB); PG8_STAGE(PG8_SB(0, 1), b2 + hstep, voffB); PG8_STAGE(PG8_SA(0, 0), a2, voffA);
;             PG8_WAIT_V(8); PG8_WAIT_L(0); PG8_BAR; PG8_MMA(1, 0, At, B0); PG8_MMA(1, 1, At, B1); PG8_BAR; PG8_SCHED;
.LBB0_355:
	s_add_i32 s80, s80, 2
	s_add_u32 s82, s62, s60
	s_addc_u32 s83, s63, s61
	ds_read_b128 v[148:151], v242
	ds_read_b128 v[152:155], v242 offset:1024
	ds_read_b128 v[156:159], v242 offset:2048
	ds_read_b128 v[160:163], v242 offset:3072
	ds_read_b128 v[164:167], v242 offset:16384
	ds_read_b128 v[168:171], v242 offset:17408
	ds_read_b128 v[172:175], v242 offset:18432
	ds_read_b128 v[176:179], v242 offset:19456
	v_lshl_add_u64 v[232:233], v[140:141], 0, s[50:51]
	s_add_i32 m0, s98, 0xc000
	ds_read_b128 v[182:185], v147
	ds_read_b128 v[186:189], v147 offset:1024
	ds_read_b128 v[208:211], v147 offset:2048
	ds_read_b128 v[212:215], v147 offset:3072
	ds_read_b128 v[216:219], v147 offset:4096
	ds_read_b128 v[220:223], v147 offset:5120
	ds_read_b128 v[224:227], v147 offset:6144
	ds_read_b128 v[228:231], v147 offset:7168
	global_load_lds_dwordx4 v[232:233], off
	v_lshl_add_u64 v[232:233], v[142:143], 0, s[50:51]
	s_add_i32 m0, s98, 0xe000
	s_nop 0
	global_load_lds_dwordx4 v[232:233], off
	s_setprio 1
	s_waitcnt vmcnt(8) lgkmcnt(0)
	s_barrier
	v_mfma_f32_16x16x32_bf16 v[126:129], v[148:151], v[182:185], 0
	v_mfma_f32_16x16x32_bf16 v[122:125], v[156:159], v[182:185], 0
	v_mfma_f32_16x16x32_bf16 v[118:121], v[148:151], v[208:211], 0
	v_mfma_f32_16x16x32_bf16 v[110:113], v[156:159], v[208:211], 0
	v_mfma_f32_16x16x32_bf16 v[102:105], v[148:151], v[216:219], 0
	v_mfma_f32_16x16x32_bf16 v[94:97], v[156:159], v[216:219], 0
	v_mfma_f32_16x16x32_bf16 v[86:89], v[148:151], v[224:227], 0
	v_mfma_f32_16x16x32_bf16 v[78:81], v[156:159], v[224:227], 0
	v_mfma_f32_16x16x32_bf16 v[126:129], v[152:155], v[186:189], v[126:129]
	v_mfma_f32_16x16x32_bf16 v[122:125], v[160:163], v[186:189], v[122:125]
	v_mfma_f32_16x16x32_bf16 v[118:121], v[152:155], v[212:215], v[118:121]
	v_mfma_f32_16x16x32_bf16 v[110:113], v[160:163], v[212:215], v[110:113]
	v_mfma_f32_16x16x32_bf16 v[102:105], v[152:155], v[220:223], v[102:105]
	v_mfma_f32_16x16x32_bf16 v[94:97], v[160:163], v[220:223], v[94:97]
	v_mfma_f32_16x16x32_bf16 v[86:89], v[152:155], v[228:231], v[86:89]
	v_mfma_f32_16x16x32_bf16 v[78:81], v[160:163], v[228:231], v[78:81]
	v_mfma_f32_16x16x32_bf16 v[114:117], v[164:167], v[182:185], 0
	v_mfma_f32_16x16x32_bf16 v[106:109], v[172:175], v[182:185], 0
	v_mfma_f32_16x16x32_bf16 v[98:101], v[164:167], v[208:211], 0
	v_mfma_f32_16x16x32_bf16 v[90:93], v[172:175], v[208:211], 0
	v_mfma_f32_16x16x32_bf16 v[82:85], v[164:167], v[216:219], 0
	v_mfma_f32_16x16x32_bf16 v[74:77], v[172:175], v[216:219], 0
	v_mfma_f32_16x16x32_bf16 v[70:73], v[164:167], v[224:227], 0
	v_mfma_f32_16x16x32_bf16 v[66:69], v[172:175], v[224:227], 0
	v_mfma_f32_16x16x32_bf16 v[114:117], v[168:171], v[186:189], v[114:117]
	v_mfma_f32_16x16x32_bf16 v[106:109], v[176:179], v[186:189], v[106:109]
	v_mfma_f32_16x16x32_bf16 v[98:101], v[168:171], v[212:215], v[98:101]
	v_mfma_f32_16x16x32_bf16 v[90:93], v[176:179], v[212:215], v[90:93]
	v_mfma_f32_16x16x32_bf16 v[82:85], v[168:171], v[220:223], v[82:85]
	v_mfma_f32_16x16x32_bf16 v[74:77], v[176:179], v[220:223], v[74:77]
	v_mfma_f32_16x16x32_bf16 v[70:73], v[168:171], v[228:231], v[70:73]
	v_mfma_f32_16x16x32_bf16 v[66:69], v[176:179], v[228:231], v[66:69]
	s_setprio 0
	s_barrier
	s_add_i32 m0, s97, 0x10000
	ds_read_b128 v[182:185], v147 offset:16384
	ds_read_b128 v[186:189], v147 offset:17408
	ds_read_b128 v[208:211], v147 offset:18432
	ds_read_b128 v[212:215], v147 offset:19456
	ds_read_b128 v[216:219], v147 offset:20480
	ds_read_b128 v[220:223], v147 offset:21504
	ds_read_b128 v[224:227], v147 offset:22528
	ds_read_b128 v[228:231], v147 offset:23552
	global_load_lds_dwordx4 v0, s[56:57]
	s_add_i32 m0, s97, 0x12000
	s_add_u32 s38, s56, s16
	s_addc_u32 s39, s57, 0
	global_load_lds_dwordx4 v134, s[56:57]
	s_add_i32 m0, s97, 0x14000
	s_nop 0
	global_load_lds_dwordx4 v0, s[38:39]
	s_add_i32 m0, s97, 0x16000
	s_nop 0
	global_load_lds_dwordx4 v134, s[38:39]
	s_mov_b32 m0, s98
	s_nop 0
	global_load_lds_dwordx4 v130, s[62:63]
	s_mov_b32 m0, s99
	s_nop 0
	global_load_lds_dwordx4 v132, s[62:63]
	s_setprio 1
	s_waitcnt vmcnt(8) lgkmcnt(0)
	s_barrier
	v_mfma_f32_16x16x32_bf16 v[62:65], v[148:151], v[182:185], 0
	v_mfma_f32_16x16x32_bf16 v[58:61], v[156:159], v[182:185], 0
	v_mfma_f32_16x16x32_bf16 v[54:57], v[148:151], v[208:211], 0
	v_mfma_f32_16x16x32_bf16 v[46:49], v[156:159], v[208:211], 0
	v_mfma_f32_16x16x32_bf16 v[38:41], v[148:151], v[216:219], 0
	v_mfma_f32_16x16x32_bf16 v[30:33], v[156:159], v[216:219], 0
	v_mfma_f32_16x16x32_bf16 v[22:25], v[148:151], v[224:227], 0
	v_mfma_f32_16x16x32_bf16 v[14:17], v[156:159], v[224:227], 0
	v_mfma_f32_16x16x32_bf16 v[62:65], v[152:155], v[186:189], v[62:65]
	v_mfma_f32_16x16x32_bf16 v[58:61], v[160:163], v[186:189], v[58:61]
	v_mfma_f32_16x16x32_bf16 v[54:57], v[152:155], v[212:215], v[54:57]
	v_mfma_f32_16x16x32_bf16 v[46:49], v[160:163], v[212:215], v[46:49]
	v_mfma_f32_16x16x32_bf16 v[38:41], v[152:155], v[220:223], v[38:41]
	v_mfma_f32_16x16x32_bf16 v[30:33], v[160:163], v[220:223], v[30:33]
	v_mfma_f32_16x16x32_bf16 v[22:25], v[152:155], v[228:231], v[22:25]
	v_mfma_f32_16x16x32_bf16 v[14:17], v[160:163], v[228:231], v[14:17]
	v_mfma_f32_16x16x32_bf16 v[50:53], v[164:167], v[182:185], 0
	v_mfma_f32_16x16x32_bf16 v[42:45], v[172:175], v[182:185], 0
	v_mfma_f32_16x16x32_bf16 v[34:37], v[164:167], v[208:211], 0
	v_mfma_f32_16x16x32_bf16 v[26:29], v[172:175], v[208:211], 0
	v_mfma_f32_16x16x32_bf16 v[18:21], v[164:167], v[216:219], 0
	v_mfma_f32_16x16x32_bf16 v[10:13], v[172:175], v[216:219], 0
	v_mfma_f32_16x16x32_bf16 v[6:9], v[164:167], v[224:227], 0
	v_mfma_f32_16x16x32_bf16 v[2:5], v[172:175], v[224:227], 0
	v_mfma_f32_16x16x32_bf16 v[50:53], v[168:171], v[186:189], v[50:53]
	v_mfma_f32_16x16x32_bf16 v[42:45], v[176:179], v[186:189], v[42:45]
	v_mfma_f32_16x16x32_bf16 v[34:37], v[168:171], v[212:215], v[34:37]
	v_mfma_f32_16x16x32_bf16 v[26:29], v[176:179], v[212:215], v[26:29]
	v_mfma_f32_16x16x32_bf16 v[18:21], v[168:171], v[220:223], v[18:21]
	v_mfma_f32_16x16x32_bf16 v[10:13], v[176:179], v[220:223], v[10:13]
	v_mfma_f32_16x16x32_bf16 v[6:9], v[168:171], v[228:231], v[6:9]
	v_mfma_f32_16x16x32_bf16 v[2:5], v[176:179], v[228:231], v[2:5]
	s_setprio 0
	s_barrier
; #define PG8_STAGE(bufoff, gbase, voff) do { _Pragma("unroll") for (int _i = 0; _i < 2; ++_i) \
;         __builtin_amdgcn_global_load_lds((const unsigned*)((const char*)(gbase) + (voff)[_i]), (PG8_LAS unsigned*)(lds + (bufoff) + ldsw + _i * 8192), 16, 0, 0); } while (0)
; #define PG8_LDA(dst, b, h) do { _Pragma("unroll") for (int m = 0; m < 4; ++m) _Pragma("unroll") for (int k = 0; k < 2; ++k) dst[m][k] = *(const PG8_LAS bf16x8*)(lds + PG8_SA(b, h) + aoff + m * 2048 + k * 1024); } while (0)
; #define PG8_LDB(dst, b, h) do { _Pragma("unroll") for (int n = 0; n < 2; ++n) _Pragma("unroll") for (int k = 0; k < 2; ++k) dst[n][k] = *(const PG8_LAS bf16x8*)(lds + PG8_SB(b, h) + boff + n * 2048 + k * 1024); } while (0)
; #define PG8_MMA(ai, bj, At, Bt) do { __builtin_amdgcn_s_setprio(1); _Pragma("unroll") for (int m = 0; m < 4; ++m) _Pragma("unroll") for (int n = 0; n < 2; ++n) _Pragma("unroll") for (int k = 0; k < 2; ++k) \
;         acc[ai][bj][m][n] = __builtin_amdgcn_mfma_f32_16x16x32_bf16(Bt[n][k], At[m][k], acc[ai][bj][m][n], 0, 0, 0); __builtin_amdgcn_s_setprio(0); } while (0)
; #define PG8_WAIT_V(n) asm volatile("s_waitcnt vmcnt(" #n ")" ::: "memory")
; #define PG8_WAIT_L(n) asm volatile("s_waitcnt lgkmcnt(" #n ")" ::: "memory")
; #define PG8_BAR __builtin_amdgcn_s_barrier()
; #define PG8_SCHED __builtin_amdgcn_sched_barrier(0)
; template <class Epi, class Sched, bool ALIGN_EPI = false, bool SP2 = false>
; __device__ __forceinline__ void gemm_phase(PG8_LAS unsigned char* lds, const Gemm g, const Sched& S, const Epi& E) {
;     ...
;             PG8_LDB(B0, 1, 0); PG8_LDB(B1, 1, 1); PG8_SCHED; PG8_LDA(At, 1, 0); PG8_STAGE(PG8_SA(0, 1), a2 + hstep, voffA);
;             PG8_WAIT_V(8); PG8_WAIT_L(0); PG8_BAR; PG8_MMA(0, 0, At, B0); PG8_MMA(0, 1, At, B1); PG8_BAR; PG8_SCHED;
;             PG8_LDA(At, 1, 1); PG8_STAGE(PG8_SB(1, 0), b3, voffB); PG8_STAGE(PG8_SB(1, 1), b3 + hstep, voffB); PG8_STAGE(PG8_SA(1, 0), a3, voffA);
;             PG8_WAIT_V(8); PG8_WAIT_L(0); PG8_BAR; PG8_MMA(1, 0, At, B0); PG8_MMA(1, 1, At, B1); PG8_BAR; PG8_SCHED;
	ds_read_b128 v[148:151], v242 offset:32768
	ds_read_b128 v[152:155], v242 offset:33792
	ds_read_b128 v[156:159], v242 offset:34816
	ds_read_b128 v[160:163], v242 offset:35840
	ds_read_b128 v[164:167], v242 offset:49152
	ds_read_b128 v[168:171], v242 offset:50176
	ds_read_b128 v[172:175], v242 offset:51200
	ds_read_b128 v[176:179], v242 offset:52224
	s_add_u32 s38, s62, s16
	s_addc_u32 s39, s63, 0
	s_mov_b32 m0, s68
	ds_read_b128 v[182:185], v147 offset:32768
	ds_read_b128 v[186:189], v147 offset:33792
	ds_read_b128 v[208:211], v147 offset:34816
	ds_read_b128 v[212:215], v147 offset:35840
	ds_read_b128 v[216:219], v147 offset:36864
	ds_read_b128 v[220:223], v147 offset:37888
	ds_read_b128 v[224:227], v147 offset:38912
	ds_read_b128 v[228:231], v147 offset:39936
	global_load_lds_dwordx4 v130, s[38:39]
	s_mov_b32 m0, s64
	s_nop 0
	global_load_lds_dwordx4 v132, s[38:39]
	s_setprio 1
	s_waitcnt vmcnt(8) lgkmcnt(0)
	s_barrier
	v_mfma_f32_16x16x32_bf16 v[126:129], v[148:151], v[182:185], v[126:129]
	v_mfma_f32_16x16x32_bf16 v[122:125], v[156:159], v[182:185], v[122:125]
	v_mfma_f32_16x16x32_bf16 v[118:121], v[148:151], v[208:211], v[118:121]
	v_mfma_f32_16x16x32_bf16 v[110:113], v[156:159], v[208:211], v[110:113]
	v_mfma_f32_16x16x32_bf16 v[102:105], v[148:151], v[216:219], v[102:105]
	v_mfma_f32_16x16x32_bf16 v[94:97], v[156:159], v[216:219], v[94:97]
	v_mfma_f32_16x16x32_bf16 v[86:89], v[148:151], v[224:227], v[86:89]
	v_mfma_f32_16x16x32_bf16 v[78:81], v[156:159], v[224:227], v[78:81]
	v_mfma_f32_16x16x32_bf16 v[126:129], v[152:155], v[186:189], v[126:129]
	v_mfma_f32_16x16x32_bf16 v[122:125], v[160:163], v[186:189], v[122:125]
	v_mfma_f32_16x16x32_bf16 v[118:121], v[152:155], v[212:215], v[118:121]
	v_mfma_f32_16x16x32_bf16 v[110:113], v[160:163], v[212:215], v[110:113]
	v_mfma_f32_16x16x32_bf16 v[102:105], v[152:155], v[220:223], v[102:105]
	v_mfma_f32_16x16x32_bf16 v[94:97], v[160:163], v[220:223], v[94:97]
	v_mfma_f32_16x16x32_bf16 v[86:89], v[152:155], v[228:231], v[86:89]
	v_mfma_f32_16x16x32_bf16 v[78:81], v[160:163], v[228:231], v[78:81]
	v_mfma_f32_16x16x32_bf16 v[114:117], v[164:167], v[182:185], v[114:117]
	v_mfma_f32_16x16x32_bf16 v[106:109], v[172:175], v[182:185], v[106:109]
	v_mfma_f32_16x16x32_bf16 v[98:101], v[164:167], v[208:211], v[98:101]
	v_mfma_f32_16x16x32_bf16 v[90:93], v[172:175], v[208:211], v[90:93]
	v_mfma_f32_16x16x32_bf16 v[82:85], v[164:167], v[216:219], v[82:85]
	v_mfma_f32_16x16x32_bf16 v[74:77], v[172:175], v[216:219], v[74:77]
	v_mfma_f32_16x16x32_bf16 v[70:73], v[164:167], v[224:227], v[70:73]
	v_mfma_f32_16x16x32_bf16 v[66:69], v[172:175], v[224:227], v[66:69]
	v_mfma_f32_16x16x32_bf16 v[114:117], v[168:171], v[186:189], v[114:117]
	v_mfma_f32_16x16x32_bf16 v[106:109], v[176:179], v[186:189], v[106:109]
	v_mfma_f32_16x16x32_bf16 v[98:101], v[168:171], v[212:215], v[98:101]
	v_mfma_f32_16x16x32_bf16 v[90:93], v[176:179], v[212:215], v[90:93]
	v_mfma_f32_16x16x32_bf16 v[82:85], v[168:171], v[220:223], v[82:85]
	v_mfma_f32_16x16x32_bf16 v[74:77], v[176:179], v[220:223], v[74:77]
	v_mfma_f32_16x16x32_bf16 v[70:73], v[168:171], v[228:231], v[70:73]
	v_mfma_f32_16x16x32_bf16 v[66:69], v[176:179], v[228:231], v[66:69]
	s_setprio 0
	s_barrier
	s_add_u32 s38, s56, s60
	s_addc_u32 s39, s57, s61
	s_add_i32 m0, s97, 0x18000
	ds_read_b128 v[182:185], v147 offset:49152
	ds_read_b128 v[186:189], v147 offset:50176
	ds_read_b128 v[208:211], v147 offset:51200
	ds_read_b128 v[212:215], v147 offset:52224
	ds_read_b128 v[216:219], v147 offset:53248
	ds_read_b128 v[220:223], v147 offset:54272
	ds_read_b128 v[224:227], v147 offset:55296
	ds_read_b128 v[228:231], v147 offset:56320
	global_load_lds_dwordx4 v0, s[38:39]
	s_add_i32 m0, s97, 0x1a000
	s_nop 0
	global_load_lds_dwordx4 v134, s[38:39]
	s_add_u32 s38, s38, s16
	s_addc_u32 s39, s39, 0
	s_add_i32 m0, s97, 0x1c000
	global_load_lds_dwordx4 v0, s[38:39]
	s_add_i32 m0, s97, 0x1e000
	s_nop 0
	global_load_lds_dwordx4 v134, s[38:39]
	s_mov_b32 m0, s72
	s_nop 0
	global_load_lds_dwordx4 v130, s[82:83]
	s_mov_b32 m0, s73
	s_nop 0
	global_load_lds_dwordx4 v132, s[82:83]
	s_add_u32 s50, s50, s48
	s_addc_u32 s51, s51, s49
	s_cmp_ge_u32 s80, s13
	s_cselect_b64 vcc, -1, 0
	s_cbranch_scc1 .Lgemm_ctl_done_p
	s_cmp_eq_u32 s88, s80
	s_cbranch_scc1 .Lgemm_ctl_last_p
	s_add_u32 s62, s18, s50
	s_addc_u32 s63, s19, s51
	s_add_u32 s56, s87, s50
	s_addc_u32 s57, s33, s51
	s_mov_b64 s[60:61], s[44:45]
	s_branch .Lgemm_ctl_join_p

; #define PG8_STAGE(bufoff, gbase, voff) do { _Pragma("unroll") for (int _i = 0; _i < 2; ++_i) \
;         __builtin_amdgcn_global_load_lds((const unsigned*)((const char*)(gbase) + (voff)[_i]), (PG8_LAS unsigned*)(lds + (bufoff) + ldsw + _i * 8192), 16, 0, 0); } while (0)
; #define PG8_LDA(dst, b, h) do { _Pragma("unroll") for (int m = 0; m < 4; ++m) _Pragma("unroll") for (int k = 0; k < 2; ++k) dst[m][k] = *(const PG8_LAS bf16x8*)(lds + PG8_SA(b, h) + aoff + m * 2048 + k * 1024); } while (0)
; #define PG8_LDB(dst, b, h) do { _Pragma("unroll") for (int n = 0; n < 2; ++n) _Pragma("unroll") for (int k = 0; k < 2; ++k) dst[n][k] = *(const PG8_LAS bf16x8*)(lds + PG8_SB(b, h) + boff + n * 2048 + k * 1024); } while (0)
; #define PG8_MMA(ai, bj, At, Bt) do { __builtin_amdgcn_s_setprio(1); _Pragma("unroll") for (int m = 0; m < 4; ++m) _Pragma("unroll") for (int n = 0; n < 2; ++n) _Pragma("unroll") for (int k = 0; k < 2; ++k) \
;         acc[ai][bj][m][n] = __builtin_amdgcn_mfma_f32_16x16x32_bf16(Bt[n][k], At[m][k], acc[ai][bj][m][n], 0, 0, 0); __builtin_amdgcn_s_setprio(0); } while (0)
; #define PG8_WAIT_V(n) asm volatile("s_waitcnt vmcnt(" #n ")" ::: "memory")
; #define PG8_WAIT_L(n) asm volatile("s_waitcnt lgkmcnt(" #n ")" ::: "memory")
; #define PG8_BAR __builtin_amdgcn_s_barrier()
; #define PG8_SCHED __builtin_amdgcn_sched_barrier(0)
; template <class Epi, class Sched, bool ALIGN_EPI = false, bool SP2 = false>
; __device__ __forceinline__ void gemm_phase(PG8_LAS unsigned char* lds, const Gemm g, const Sched& S, const Epi& E) {
;     ...
;             PG8_LDB(B0, 0, 0); PG8_LDB(B1, 0, 1); PG8_SCHED; PG8_LDA(At, 0, 0); PG8_STAGE(PG8_SA(1, 1), a1 + hstep, voffA);
;             PG8_WAIT_V(8); PG8_WAIT_L(0); PG8_BAR; PG8_MMA(0, 0, At, B0); PG8_MMA(0, 1, At, B1); PG8_BAR; PG8_SCHED;
;     ...
;             PG8_WAIT_V(8); PG8_WAIT_L(0); PG8_BAR; PG8_MMA(1, 0, At, B0); PG8_MMA(1, 1, At, B1); PG8_BAR; PG8_SCHED;
.Lgemm_ctl_done_p:
	s_setprio 1
	s_waitcnt vmcnt(8) lgkmcnt(0)
	s_barrier
	v_mfma_f32_16x16x32_bf16 v[62:65], v[148:151], v[182:185], v[62:65]
	v_mfma_f32_16x16x32_bf16 v[58:61], v[156:159], v[182:185], v[58:61]
	v_mfma_f32_16x16x32_bf16 v[54:57], v[148:151], v[208:211], v[54:57]
	v_mfma_f32_16x16x32_bf16 v[46:49], v[156:159], v[208:211], v[46:49]
	v_mfma_f32_16x16x32_bf16 v[38:41], v[148:151], v[216:219], v[38:41]
	v_mfma_f32_16x16x32_bf16 v[30:33], v[156:159], v[216:219], v[30:33]
	v_mfma_f32_16x16x32_bf16 v[22:25], v[148:151], v[224:227], v[22:25]
	v_mfma_f32_16x16x32_bf16 v[14:17], v[156:159], v[224:227], v[14:17]
	v_mfma_f32_16x16x32_bf16 v[62:65], v[152:155], v[186:189], v[62:65]
	v_mfma_f32_16x16x32_bf16 v[58:61], v[160:163], v[186:189], v[58:61]
	v_mfma_f32_16x16x32_bf16 v[54:57], v[152:155], v[212:215], v[54:57]
	v_mfma_f32_16x16x32_bf16 v[46:49], v[160:163], v[212:215], v[46:49]
	v_mfma_f32_16x16x32_bf16 v[38:41], v[152:155], v[220:223], v[38:41]
	v_mfma_f32_16x16x32_bf16 v[30:33], v[160:163], v[220:223], v[30:33]
	v_mfma_f32_16x16x32_bf16 v[22:25], v[152:155], v[228:231], v[22:25]
	v_mfma_f32_16x16x32_bf16 v[14:17], v[160:163], v[228:231], v[14:17]
	v_mfma_f32_16x16x32_bf16 v[50:53], v[164:167], v[182:185], v[50:53]
	v_mfma_f32_16x16x32_bf16 v[42:45], v[172:175], v[182:185], v[42:45]
	v_mfma_f32_16x16x32_bf16 v[34:37], v[164:167], v[208:211], v[34:37]
	v_mfma_f32_16x16x32_bf16 v[26:29], v[172:175], v[208:211], v[26:29]
	v_mfma_f32_16x16x32_bf16 v[18:21], v[164:167], v[216:219], v[18:21]
	v_mfma_f32_16x16x32_bf16 v[10:13], v[172:175], v[216:219], v[10:13]
	v_mfma_f32_16x16x32_bf16 v[6:9], v[164:167], v[224:227], v[6:9]
	v_mfma_f32_16x16x32_bf16 v[2:5], v[172:175], v[224:227], v[2:5]
	v_mfma_f32_16x16x32_bf16 v[50:53], v[168:171], v[186:189], v[50:53]
	v_mfma_f32_16x16x32_bf16 v[42:45], v[176:179], v[186:189], v[42:45]
	v_mfma_f32_16x16x32_bf16 v[34:37], v[168:171], v[212:215], v[34:37]
	v_mfma_f32_16x16x32_bf16 v[26:29], v[176:179], v[212:215], v[26:29]
	v_mfma_f32_16x16x32_bf16 v[18:21], v[168:171], v[220:223], v[18:21]
	v_mfma_f32_16x16x32_bf16 v[10:13], v[176:179], v[220:223], v[10:13]
	v_mfma_f32_16x16x32_bf16 v[6:9], v[168:171], v[228:231], v[6:9]
	v_mfma_f32_16x16x32_bf16 v[2:5], v[176:179], v[228:231], v[2:5]
	s_setprio 0
	s_barrier
	s_cbranch_vccz .Lgemm_head
	s_branch .LBB0_360
.Lgemm_head:
	ds_read_b128 v[148:151], v242
	ds_read_b128 v[152:155], v242 offset:1024
	ds_read_b128 v[156:159], v242 offset:2048
	ds_read_b128 v[160:163], v242 offset:3072
	ds_read_b128 v[164:167], v242 offset:16384
	ds_read_b128 v[168:171], v242 offset:17408
	ds_read_b128 v[172:175], v242 offset:18432
	ds_read_b128 v[176:179], v242 offset:19456
	v_lshl_add_u64 v[232:233], v[140:141], 0, s[50:51]
	s_add_i32 m0, s98, 0xc000
	ds_read_b128 v[182:185], v147
	ds_read_b128 v[186:189], v147 offset:1024
	ds_read_b128 v[208:211], v147 offset:2048
	ds_read_b128 v[212:215], v147 offset:3072
	ds_read_b128 v[216:219], v147 offset:4096
	ds_read_b128 v[220:223], v147 offset:5120
	ds_read_b128 v[224:227], v147 offset:6144
	ds_read_b128 v[228:231], v147 offset:7168
	global_load_lds_dwordx4 v[232:233], off
	v_lshl_add_u64 v[232:233], v[142:143], 0, s[50:51]
	s_add_i32 m0, s98, 0xe000
	s_nop 0
	global_load_lds_dwordx4 v[232:233], off
	s_setprio 1
	s_waitcnt vmcnt(8) lgkmcnt(0)
	s_barrier
	v_mfma_f32_16x16x32_bf16 v[126:129], v[148:151], v[182:185], v[126:129]
	v_mfma_f32_16x16x32_bf16 v[122:125], v[156:159], v[182:185], v[122:125]
	v_mfma_f32_16x16x32_bf16 v[118:121], v[148:151], v[208:211], v[118:121]
	v_mfma_f32_16x16x32_bf16 v[110:113], v[156:159], v[208:211], v[110:113]
	v_mfma_f32_16x16x32_bf16 v[102:105], v[148:151], v[216:219], v[102:105]
	v_mfma_f32_16x16x32_bf16 v[94:97], v[156:159], v[216:219], v[94:97]
	v_mfma_f32_16x16x32_bf16 v[86:89], v[148:151], v[224:227], v[86:89]
	v_mfma_f32_16x16x32_bf16 v[78:81], v[156:159], v[224:227], v[78:81]
	v_mfma_f32_16x16x32_bf16 v[126:129], v[152:155], v[186:189], v[126:129]
	v_mfma_f32_16x16x32_bf16 v[122:125], v[160:163], v[186:189], v[122:125]
	v_mfma_f32_16x16x32_bf16 v[118:121], v[152:155], v[212:215], v[118:121]
	v_mfma_f32_16x16x32_bf16 v[110:113], v[160:163], v[212:215], v[110:113]
	v_mfma_f32_16x16x32_bf16 v[102:105], v[152:155], v[220:223], v[102:105]
	v_mfma_f32_16x16x32_bf16 v[94:97], v[160:163], v[220:223], v[94:97]
	v_mfma_f32_16x16x32_bf16 v[86:89], v[152:155], v[228:231], v[86:89]
	v_mfma_f32_16x16x32_bf16 v[78:81], v[160:163], v[228:231], v[78:81]
	v_mfma_f32_16x16x32_bf16 v[114:117], v[164:167], v[182:185], v[114:117]
	v_mfma_f32_16x16x32_bf16 v[106:109], v[172:175], v[182:185], v[106:109]
	v_mfma_f32_16x16x32_bf16 v[98:101], v[164:167], v[208:211], v[98:101]
	v_mfma_f32_16x16x32_bf16 v[90:93], v[172:175], v[208:211], v[90:93]
	v_mfma_f32_16x16x32_bf16 v[82:85], v[164:167], v[216:219], v[82:85]
	v_mfma_f32_16x16x32_bf16 v[74:77], v[172:175], v[216:219], v[74:77]
	v_mfma_f32_16x16x32_bf16 v[70:73], v[164:167], v[224:227], v[70:73]
	v_mfma_f32_16x16x32_bf16 v[66:69], v[172:175], v[224:227], v[66:69]
	v_mfma_f32_16x16x32_bf16 v[114:117], v[168:171], v[186:189], v[114:117]
	v_mfma_f32_16x16x32_bf16 v[106:109], v[176:179], v[186:189], v[106:109]
	v_mfma_f32_16x16x32_bf16 v[98:101], v[168:171], v[212:215], v[98:101]
	v_mfma_f32_16x16x32_bf16 v[90:93], v[176:179], v[212:215], v[90:93]
	v_mfma_f32_16x16x32_bf16 v[82:85], v[168:171], v[220:223], v[82:85]
	v_mfma_f32_16x16x32_bf16 v[74:77], v[176:179], v[220:223], v[74:77]
	v_mfma_f32_16x16x32_bf16 v[70:73], v[168:171], v[228:231], v[70:73]
	v_mfma_f32_16x16x32_bf16 v[66:69], v[176:179], v[228:231], v[66:69]
	s_setprio 0
	s_barrier
; #define PG8_STAGE(bufoff, gbase, voff) do { _Pragma("unroll") for (int _i = 0; _i < 2; ++_i) \
;         __builtin_amdgcn_global_load_lds((const unsigned*)((const char*)(gbase) + (voff)[_i]), (PG8_LAS unsigned*)(lds + (bufoff) + ldsw + _i * 8192), 16, 0, 0); } while (0)
; #define PG8_LDA(dst, b, h) do { _Pragma("unroll") for (int m = 0; m < 4; ++m) _Pragma("unroll") for (int k = 0; k < 2; ++k) dst[m][k] = *(const PG8_LAS bf16x8*)(lds + PG8_SA(b, h) + aoff + m * 2048 + k * 1024); } while (0)
; #define PG8_LDB(dst, b, h) do { _Pragma("unroll") for (int n = 0; n < 2; ++n) _Pragma("unroll") for (int k = 0; k < 2; ++k) dst[n][k] = *(const PG8_LAS bf16x8*)(lds + PG8_SB(b, h) + boff + n * 2048 + k * 1024); } while (0)
; #define PG8_MMA(ai, bj, At, Bt) do { __builtin_amdgcn_s_setprio(1); _Pragma("unroll") for (int m = 0; m < 4; ++m) _Pragma("unroll") for (int n = 0; n < 2; ++n) _Pragma("unroll") for (int k = 0; k < 2; ++k) \
;         acc[ai][bj][m][n] = __builtin_amdgcn_mfma_f32_16x16x32_bf16(Bt[n][k], At[m][k], acc[ai][bj][m][n], 0, 0, 0); __builtin_amdgcn_s_setprio(0); } while (0)
; #define PG8_WAIT_V(n) asm volatile("s_waitcnt vmcnt(" #n ")" ::: "memory")
; #define PG8_WAIT_L(n) asm volatile("s_waitcnt lgkmcnt(" #n ")" ::: "memory")
; #define PG8_BAR __builtin_amdgcn_s_barrier()
; #define PG8_SCHED __builtin_amdgcn_sched_barrier(0)
; template <class Epi, class Sched, bool ALIGN_EPI = false, bool SP2 = false>
; __device__ __forceinline__ void gemm_phase(PG8_LAS unsigned char* lds, const Gemm g, const Sched& S, const Epi& E) {
;     ...
;             PG8_LDA(At, 0, 1); PG8_STAGE(PG8_SB(0, 0), b2, voffB); PG8_STAGE(PG8_SB(0, 1), b2 + hstep, voffB); PG8_STAGE(PG8_SA(0, 0), a2, voffA);
;             PG8_WAIT_V(8); PG8_WAIT_L(0); PG8_BAR; PG8_MMA(1, 0, At, B0); PG8_MMA(1, 1, At, B1); PG8_BAR; PG8_SCHED;
;             PG8_LDB(B0, 1, 0); PG8_LDB(B1, 1, 1); PG8_SCHED; PG8_LDA(At, 1, 0); PG8_STAGE(PG8_SA(0, 1), a2 + hstep, voffA);
	s_add_i32 m0, s97, 0x10000
	ds_read_b128 v[182:185], v147 offset:16384
	ds_read_b128 v[186:189], v147 offset:17408
	ds_read_b128 v[208:211], v147 offset:18432
	ds_read_b128 v[212:215], v147 offset:19456
	ds_read_b128 v[216:219], v147 offset:20480
	ds_read_b128 v[220:223], v147 offset:21504
	ds_read_b128 v[224:227], v147 offset:22528
	ds_read_b128 v[228:231], v147 offset:23552
	global_load_lds_dwordx4 v0, s[56:57]
	s_add_i32 m0, s97, 0x12000
	s_add_u32 s38, s56, s16
	s_addc_u32 s39, s57, 0
	global_load_lds_dwordx4 v134, s[56:57]
	s_add_i32 m0, s97, 0x14000
	s_nop 0
	global_load_lds_dwordx4 v0, s[38:39]
	s_add_i32 m0, s97, 0x16000
	s_nop 0
	global_load_lds_dwordx4 v134, s[38:39]
	s_mov_b32 m0, s98
	s_nop 0
	global_load_lds_dwordx4 v130, s[62:63]
	s_mov_b32 m0, s99
	s_nop 0
	global_load_lds_dwordx4 v132, s[62:63]
	s_setprio 1
	s_waitcnt vmcnt(8) lgkmcnt(0)
	s_barrier
	v_mfma_f32_16x16x32_bf16 v[62:65], v[148:151], v[182:185], v[62:65]
	v_mfma_f32_16x16x32_bf16 v[58:61], v[156:159], v[182:185], v[58:61]
	v_mfma_f32_16x16x32_bf16 v[54:57], v[148:151], v[208:211], v[54:57]
	v_mfma_f32_16x16x32_bf16 v[46:49], v[156:159], v[208:211], v[46:49]
	v_mfma_f32_16x16x32_bf16 v[38:41], v[148:151], v[216:219], v[38:41]
	v_mfma_f32_16x16x32_bf16 v[30:33], v[156:159], v[216:219], v[30:33]
	v_mfma_f32_16x16x32_bf16 v[22:25], v[148:151], v[224:227], v[22:25]
	v_mfma_f32_16x16x32_bf16 v[14:17], v[156:159], v[224:227], v[14:17]
	v_mfma_f32_16x16x32_bf16 v[62:65], v[152:155], v[186:189], v[62:65]
	v_mfma_f32_16x16x32_bf16 v[58:61], v[160:163], v[186:189], v[58:61]
	v_mfma_f32_16x16x32_bf16 v[54:57], v[152:155], v[212:215], v[54:57]
	v_mfma_f32_16x16x32_bf16 v[46:49], v[160:163], v[212:215], v[46:49]
	v_mfma_f32_16x16x32_bf16 v[38:41], v[152:155], v[220:223], v[38:41]
	v_mfma_f32_16x16x32_bf16 v[30:33], v[160:163], v[220:223], v[30:33]
	v_mfma_f32_16x16x32_bf16 v[22:25], v[152:155], v[228:231], v[22:25]
	v_mfma_f32_16x16x32_bf16 v[14:17], v[160:163], v[228:231], v[14:17]
	v_mfma_f32_16x16x32_bf16 v[50:53], v[164:167], v[182:185], v[50:53]
	v_mfma_f32_16x16x32_bf16 v[42:45], v[172:175], v[182:185], v[42:45]
	v_mfma_f32_16x16x32_bf16 v[34:37], v[164:167], v[208:211], v[34:37]
	v_mfma_f32_16x16x32_bf16 v[26:29], v[172:175], v[208:211], v[26:29]
	v_mfma_f32_16x16x32_bf16 v[18:21], v[164:167], v[216:219], v[18:21]
	v_mfma_f32_16x16x32_bf16 v[10:13], v[172:175], v[216:219], v[10:13]
	v_mfma_f32_16x16x32_bf16 v[6:9], v[164:167], v[224:227], v[6:9]
	v_mfma_f32_16x16x32_bf16 v[2:5], v[172:175], v[224:227], v[2:5]
	v_mfma_f32_16x16x32_bf16 v[50:53], v[168:171], v[186:189], v[50:53]
	v_mfma_f32_16x16x32_bf16 v[42:45], v[176:179], v[186:189], v[42:45]
	v_mfma_f32_16x16x32_bf16 v[34:37], v[168:171], v[212:215], v[34:37]
	v_mfma_f32_16x16x32_bf16 v[26:29], v[176:179], v[212:215], v[26:29]
	v_mfma_f32_16x16x32_bf16 v[18:21], v[168:171], v[220:223], v[18:21]
	v_mfma_f32_16x16x32_bf16 v[10:13], v[176:179], v[220:223], v[10:13]
	v_mfma_f32_16x16x32_bf16 v[6:9], v[168:171], v[228:231], v[6:9]
	v_mfma_f32_16x16x32_bf16 v[2:5], v[176:179], v[228:231], v[2:5]
	s_setprio 0
	s_barrier
	ds_read_b128 v[148:151], v242 offset:32768
	ds_read_b128 v[152:155], v242 offset:33792
	ds_read_b128 v[156:159], v242 offset:34816
	ds_read_b128 v[160:163], v242 offset:35840
	ds_read_b128 v[164:167], v242 offset:49152
	ds_read_b128 v[168:171], v242 offset:50176
	ds_read_b128 v[172:175], v242 offset:51200
	ds_read_b128 v[176:179], v242 offset:52224
	s_add_u32 s38, s62, s16
	s_addc_u32 s39, s63, 0
	s_mov_b32 m0, s68
	ds_read_b128 v[182:185], v147 offset:32768
	ds_read_b128 v[186:189], v147 offset:33792
	ds_read_b128 v[208:211], v147 offset:34816
	ds_read_b128 v[212:215], v147 offset:35840
	ds_read_b128 v[216:219], v147 offset:36864
	ds_read_b128 v[220:223], v147 offset:37888
	ds_read_b128 v[224:227], v147 offset:38912
	ds_read_b128 v[228:231], v147 offset:39936
	global_load_lds_dwordx4 v130, s[38:39]
	s_mov_b32 m0, s64
	s_nop 0
	global_load_lds_dwordx4 v132, s[38:39]
	s_setprio 1
	s_waitcnt vmcnt(8) lgkmcnt(0)
	s_barrier
; #define PG8_STAGE(bufoff, gbase, voff) do { _Pragma("unroll") for (int _i = 0; _i < 2; ++_i) \
;         __builtin_amdgcn_global_load_lds((const unsigned*)((const char*)(gbase) + (voff)[_i]), (PG8_LAS unsigned*)(lds + (bufoff) + ldsw + _i * 8192), 16, 0, 0); } while (0)
; #define PG8_LDA(dst, b, h) do { _Pragma("unroll") for (int m = 0; m < 4; ++m) _Pragma("unroll") for (int k = 0; k < 2; ++k) dst[m][k] = *(const PG8_LAS bf16x8*)(lds + PG8_SA(b, h) + aoff + m * 2048 + k * 1024); } while (0)
; #define PG8_MMA(ai, bj, At, Bt) do { __builtin_amdgcn_s_setprio(1); _Pragma("unroll") for (int m = 0; m < 4; ++m) _Pragma("unroll") for (int n = 0; n < 2; ++n) _Pragma("unroll") for (int k = 0; k < 2; ++k) \
;         acc[ai][bj][m][n] = __builtin_amdgcn_mfma_f32_16x16x32_bf16(Bt[n][k], At[m][k], acc[ai][bj][m][n], 0, 0, 0); __builtin_amdgcn_s_setprio(0); } while (0)
; #define PG8_WAIT_V(n) asm volatile("s_waitcnt vmcnt(" #n ")" ::: "memory")
; #define PG8_WAIT_L(n) asm volatile("s_waitcnt lgkmcnt(" #n ")" ::: "memory")
; #define PG8_BAR __builtin_amdgcn_s_barrier()
; #define PG8_SCHED __builtin_amdgcn_sched_barrier(0)
; template <class Epi, class Sched, bool ALIGN_EPI = false, bool SP2 = false>
; __device__ __forceinline__ void gemm_phase(PG8_LAS unsigned char* lds, const Gemm g, const Sched& S, const Epi& E) {
;     ...
;             PG8_WAIT_V(8); PG8_WAIT_L(0); PG8_BAR; PG8_MMA(0, 0, At, B0); PG8_MMA(0, 1, At, B1); PG8_BAR; PG8_SCHED;
;             PG8_LDA(At, 1, 1); PG8_STAGE(PG8_SB(1, 0), b3, voffB); PG8_STAGE(PG8_SB(1, 1), b3 + hstep, voffB); PG8_STAGE(PG8_SA(1, 0), a3, voffA);
;             PG8_WAIT_V(8); PG8_WAIT_L(0); PG8_BAR; PG8_MMA(1, 0, At, B0); PG8_MMA(1, 1, At, B1); PG8_BAR; PG8_SCHED;
	v_mfma_f32_16x16x32_bf16 v[126:129], v[148:151], v[182:185], v[126:129]
	v_mfma_f32_16x16x32_bf16 v[122:125], v[156:159], v[182:185], v[122:125]
	v_mfma_f32_16x16x32_bf16 v[118:121], v[148:151], v[208:211], v[118:121]
	v_mfma_f32_16x16x32_bf16 v[110:113], v[156:159], v[208:211], v[110:113]
	v_mfma_f32_16x16x32_bf16 v[102:105], v[148:151], v[216:219], v[102:105]
	v_mfma_f32_16x16x32_bf16 v[94:97], v[156:159], v[216:219], v[94:97]
	v_mfma_f32_16x16x32_bf16 v[86:89], v[148:151], v[224:227], v[86:89]
	v_mfma_f32_16x16x32_bf16 v[78:81], v[156:159], v[224:227], v[78:81]
	v_mfma_f32_16x16x32_bf16 v[126:129], v[152:155], v[186:189], v[126:129]
	v_mfma_f32_16x16x32_bf16 v[122:125], v[160:163], v[186:189], v[122:125]
	v_mfma_f32_16x16x32_bf16 v[118:121], v[152:155], v[212:215], v[118:121]
	v_mfma_f32_16x16x32_bf16 v[110:113], v[160:163], v[212:215], v[110:113]
	v_mfma_f32_16x16x32_bf16 v[102:105], v[152:155], v[220:223], v[102:105]
	v_mfma_f32_16x16x32_bf16 v[94:97], v[160:163], v[220:223], v[94:97]
	v_mfma_f32_16x16x32_bf16 v[86:89], v[152:155], v[228:231], v[86:89]
	v_mfma_f32_16x16x32_bf16 v[78:81], v[160:163], v[228:231], v[78:81]
	v_mfma_f32_16x16x32_bf16 v[114:117], v[164:167], v[182:185], v[114:117]
	v_mfma_f32_16x16x32_bf16 v[106:109], v[172:175], v[182:185], v[106:109]
	v_mfma_f32_16x16x32_bf16 v[98:101], v[164:167], v[208:211], v[98:101]
	v_mfma_f32_16x16x32_bf16 v[90:93], v[172:175], v[208:211], v[90:93]
	v_mfma_f32_16x16x32_bf16 v[82:85], v[164:167], v[216:219], v[82:85]
	v_mfma_f32_16x16x32_bf16 v[74:77], v[172:175], v[216:219], v[74:77]
	v_mfma_f32_16x16x32_bf16 v[70:73], v[164:167], v[224:227], v[70:73]
	v_mfma_f32_16x16x32_bf16 v[66:69], v[172:175], v[224:227], v[66:69]
	v_mfma_f32_16x16x32_bf16 v[114:117], v[168:171], v[186:189], v[114:117]
	v_mfma_f32_16x16x32_bf16 v[106:109], v[176:179], v[186:189], v[106:109]
	v_mfma_f32_16x16x32_bf16 v[98:101], v[168:171], v[212:215], v[98:101]
	v_mfma_f32_16x16x32_bf16 v[90:93], v[176:179], v[212:215], v[90:93]
	v_mfma_f32_16x16x32_bf16 v[82:85], v[168:171], v[220:223], v[82:85]
	v_mfma_f32_16x16x32_bf16 v[74:77], v[176:179], v[220:223], v[74:77]
	v_mfma_f32_16x16x32_bf16 v[70:73], v[168:171], v[228:231], v[70:73]
	v_mfma_f32_16x16x32_bf16 v[66:69], v[176:179], v[228:231], v[66:69]
	s_setprio 0
	s_barrier
	s_add_u32 s38, s56, s60
	s_addc_u32 s39, s57, s61
	s_add_i32 m0, s97, 0x18000
	ds_read_b128 v[182:185], v147 offset:49152
	ds_read_b128 v[186:189], v147 offset:50176
	ds_read_b128 v[208:211], v147 offset:51200
	ds_read_b128 v[212:215], v147 offset:52224
	ds_read_b128 v[216:219], v147 offset:53248
	ds_read_b128 v[220:223], v147 offset:54272
	ds_read_b128 v[224:227], v147 offset:55296
	ds_read_b128 v[228:231], v147 offset:56320
	global_load_lds_dwordx4 v0, s[38:39]
	s_add_i32 m0, s97, 0x1a000
	s_nop 0
	global_load_lds_dwordx4 v134, s[38:39]
	s_add_u32 s38, s38, s16
	s_addc_u32 s39, s39, 0
	s_add_i32 m0, s97, 0x1c000
	global_load_lds_dwordx4 v0, s[38:39]
	s_add_i32 m0, s97, 0x1e000
	s_nop 0
	global_load_lds_dwordx4 v134, s[38:39]
	s_mov_b32 m0, s72
	s_nop 0
	global_load_lds_dwordx4 v130, s[82:83]
	s_mov_b32 m0, s73
	s_nop 0
	global_load_lds_dwordx4 v132, s[82:83]
	s_add_u32 s50, s50, s48
	s_addc_u32 s51, s51, s49
	s_cmp_ge_u32 s80, s13
	s_cselect_b64 vcc, -1, 0
	s_cbranch_scc1 .Lgemm_ctl_done
	s_cmp_eq_u32 s88, s80
	s_cbranch_scc1 .Lgemm_ctl_last
	s_add_u32 s62, s18, s50
	s_addc_u32 s63, s19, s51
	s_add_u32 s56, s87, s50
	s_addc_u32 s57, s33, s51
	s_mov_b64 s[60:61], s[44:45]
	s_branch .Lgemm_ctl_join
